# move DA K buffer out of the HN alias (fixes a latent WAR race: in-proj epilogue wrote K over HN rows other tiles still read); K/KM/VTM offsets permuted
# baseline (speedup 1.0000x reference)
; DI int bid_l() { int t = blockIdx.x; asm volatile("" : "+s"(t)); return t; }
; DI void ph_attn(const Params& p, char* lds, bool need_ctx) {
;   char* ws = p.ws;
;   u16* oa = (u16*)(ws + OFF_OA); u16* mix = (u16*)(ws + OFF_MIXO);
;   const int n_lat = 8 * 12 * 32, n_all = n_lat + (need_ctx ? 8 * 12 * 2 : 0);
;   const float sa = 0.125f * 1.4426950408889634f;
;   const float sm = 0.10206207261596575f * 1.4426950408889634f;
;   for (int it = bid_l(); it < n_all; it += gridDim.x) {
;     int b, head, qb; bool isl;
;     if (it < n_lat) {
;       isl = true;
;       int pr;
;       if (gridDim.x == 512) {
;         const int bid = it & 511, rnd = it >> 9, xcd = bid & 7, slot = bid >> 3;
;         pr = rnd * 16 + xcd * 2 + (slot >> 5); qb = slot & 31;
;       } else { qb = it & 31; pr = it >> 5; }
;       head = 11 - (pr % 12); b = pr / 12;
;     }
;     else { isl = false; const int q = it - n_lat; qb = q & 1; const int r = q >> 1; head = 11 - (r % 12); b = r / 12; }
;     const int kt_lo = isl ? 0 : 64, kt_hi = 68;
;     const size_t orow0 = isl ? (size_t)b * 4096 : (size_t)TL + (size_t)b * 256;
;     if (head >= 8) {
;       const int hm = head - 8;
;       const u16* Q = isl ? (const u16*)(ws + OFF_QM) + (size_t)(b * 4 + hm) * 4096 * 96 : (const u16*)(ws + OFF_QMC) + (size_t)(b * 4 + hm) * 256 * 96;
;       const u16* K = (const u16*)(ws + OFF_KM) + (size_t)(b * 4 + hm) * KPOS * 96;
;       const u16* V = (const u16*)(ws + OFF_VTM) + (size_t)(b * 4 + hm) * 128 * KPOS;
;       attn_item<96>(lds, Q, K, V, qb * 128, kt_lo, kt_hi, sm, mix + orow0 * D + 512 + hm * 128, D);
;     } else {
;       const u16* Q = isl ? (const u16*)(ws + OFF_QA) + (size_t)(b * 8 + head) * 4096 * 64 : (const u16*)(ws + OFF_QAC) + (size_t)(b * 8 + head) * 256 * 64;
;       const u16* K = (const u16*)(ws + OFF_KA) + (size_t)(b * 8 + head) * KPOS * 64;
;       const u16* V = (const u16*)(ws + OFF_VTA) + (size_t)(b * 4 + (head & 3)) * 128 * KPOS;
;       attn_item<64>(lds, Q, K, V, qb * 128, kt_lo, kt_hi, sa, oa + orow0 * D + head * 128, D);
.LBB0_359:
	s_and_b64 vcc, exec, s[2:3]
	s_cbranch_vccz .LBB0_366
	v_readlane_b32 s40, v253, 38
	v_readlane_b32 s42, v253, 39
	s_cmp_gt_i32 s40, 1
	s_mov_b64 s[0:1], -1
	v_readlane_b32 s43, v253, 40
	s_cbranch_scc0 .LBB0_623
	s_cmp_gt_i32 s40, 2
	s_cbranch_scc0 .LBB0_816
	s_cmp_gt_i32 s40, 3
	s_cbranch_scc0 .LBB0_734
	v_readlane_b32 s2, v253, 33
	v_readlane_b32 s3, v253, 34
	s_and_b64 vcc, exec, s[2:3]
	s_cbranch_vccz .LBB0_714
	v_readlane_b32 s0, v253, 31
	v_readlane_b32 s1, v253, 32
	s_and_b64 s[0:1], s[0:1], exec
	s_movk_i32 s0, 0xcc0
	s_cselect_b32 s8, s0, 0xc00
	v_readlane_b32 s9, v251, 0
	s_cmp_ge_i32 s9, s8
	s_cbranch_scc1 .LBB0_713
	s_add_u32 s10, s30, 0x37ac000
	s_addc_u32 s11, s31, 0
	s_add_u32 s12, s30, 0x18bac000
	s_addc_u32 s13, s31, 0
	s_add_u32 s14, s30, 0x169ac000
	s_addc_u32 s15, s31, 0
	s_add_u32 s16, s30, 0x1adac000
	s_addc_u32 s17, s31, 0
	s_add_u32 s18, s30, 0x147ac000
	s_addc_u32 s19, s31, 0
	s_branch .LBB0_626

; DI int tid_l() { int t = threadIdx.x; asm volatile("" : "+v"(t)); return t; }
; DI f32x16 zero16() { f32x16 z; for (int i = 0; i < 16; ++i) z[i] = 0.f; return z; }
; template <int DQ>
; DI void attn_item(char* lds, const u16* __restrict__ Qb, const u16* __restrict__ Kb, const u16* __restrict__ Vtb,
;                   int q0, int kt_lo, int kt_hi, float sc, u16* __restrict__ Ob, int ldo) {
;   constexpr int KS = DQ + 8, KCH = DQ / 8, KPT = 64 * KCH / 256, NKK = DQ / 16;
;   u16* sK = (u16*)lds;
;   u16* sV = sK + 64 * KS;
;   const int tid = tid_l(), lane = tid & 63, w = tid >> 6, l31 = lane & 31, h = lane >> 5;
;   bf16x8 qf[NKK];
;   {
;     const u16* qrow = Qb + (size_t)(q0 + w * 32 + l31) * DQ + h * 8;
; #pragma unroll
;     for (int kk = 0; kk < NKK; ++kk) qf[kk] = *(const bf16x8*)(qrow + kk * 16);
;   }
;   u32x4 rk[KPT], rv[4];
;     ...
;   f32x16 o[4];
; #pragma unroll
;   for (int i = 0; i < 4; ++i) o[i] = zero16();
;   float m_run = -INFINITY, l_run = 0.f;
;   constexpr int STG = 64 * KS + 128 * 72;
;     ...
;   ATT_LOAD(kt_lo)
;   ATT_STORE(0)
;   if (kt_lo + 1 < kt_hi) ATT_LOAD(kt_lo + 1)
.LBB0_634:
	s_ashr_i32 s5, s4, 31
	s_lshl_b64 s[0:1], s[4:5], 12
	s_lshl_b64 s[6:7], s[4:5], 8
	s_add_u32 s5, s6, 0x8000
	s_addc_u32 s23, s7, 0
	s_and_b64 s[6:7], s[2:3], exec
	s_cselect_b32 s1, s1, s23
	s_cselect_b32 s0, s0, s5
	s_cmp_gt_i32 s22, 3
	s_mov_b64 s[6:7], -1
	s_cbranch_scc0 .LBB0_644
	s_sub_i32 s5, 11, s22
	s_lshl_b32 s6, s4, 3
	s_add_i32 s6, s6, s5
	s_ashr_i32 s7, s6, 31
	s_and_b64 s[24:25], s[2:3], exec
	s_mov_b32 s23, 0x105cc000
	s_cselect_b32 s23, s23, 0x125cc000
	s_add_u32 s23, s30, s23
	s_addc_u32 s26, s31, 0
	s_and_b64 s[24:25], s[2:3], exec
	s_cselect_b32 s24, 19, 15
	s_lshl_b64 s[24:25], s[6:7], s24
	s_add_u32 s28, s23, s24
	s_addc_u32 s29, s26, s25
	s_mul_i32 s24, s6, 0x88000
	s_mul_hi_i32 s23, s6, 0x88000
	s_add_u32 s6, s12, s24
	s_addc_u32 s7, s13, s23
	s_lshl_b32 s25, s4, 2
	s_and_b32 s26, s5, 3
	v_mov_b32_e32 v46, v0
	s_or_b32 s26, s25, s26
	s_mul_hi_i32 s25, s26, 0x110000
	v_ashrrev_i32_e32 v4, 31, v46
	s_mul_i32 s26, s26, 0x110000
	v_lshrrev_b32_e32 v4, 29, v4
	s_add_u32 s27, s14, s26
	v_add_u32_e32 v4, v46, v4
	s_addc_u32 s34, s15, s25
	s_lshl_b32 s35, s20, 6
	v_ashrrev_i32_e32 v48, 3, v4
	v_and_b32_e32 v4, -8, v4
	v_sub_u32_e32 v49, v46, v4
	v_add_u32_e32 v4, s35, v48
	v_ashrrev_i32_e32 v5, 31, v4
	v_lshlrev_b64 v[6:7], 7, v[4:5]
	v_add_u32_e32 v5, 0x100, v46
	v_ashrrev_i32_e32 v10, 31, v5
	v_lshrrev_b32_e32 v10, 29, v10
	v_add_u32_e32 v10, v5, v10
	v_ashrrev_i32_e32 v50, 3, v10
	v_and_b32_e32 v10, -8, v10
	v_lshlrev_b32_e32 v8, 3, v49
	v_sub_u32_e32 v51, v5, v10
	v_add_u32_e32 v32, s35, v50
	v_ashrrev_i32_e32 v9, 31, v8
	v_ashrrev_i32_e32 v33, 31, v32
	s_waitcnt vmcnt(1)
	v_lshlrev_b32_e32 v12, 3, v51
	v_lshl_add_u64 v[6:7], s[6:7], 0, v[6:7]
	v_lshlrev_b64 v[30:31], 1, v[8:9]
	v_lshlrev_b64 v[10:11], 7, v[32:33]
	v_ashrrev_i32_e32 v13, 31, v12
	v_and_b32_e32 v47, 31, v46
	v_ashrrev_i32_e32 v2, 1, v46
	v_lshl_add_u64 v[6:7], v[6:7], 0, v[30:31]
	v_lshl_add_u64 v[10:11], s[6:7], 0, v[10:11]
	v_lshlrev_b64 v[34:35], 1, v[12:13]
	v_and_b32_e32 v2, 0xffffffe0, v2
	v_lshl_or_b32 v14, s21, 7, v47
	global_load_dwordx4 v[6:9], v[6:7], off
	v_lshl_add_u64 v[10:11], v[10:11], 0, v[34:35]
	global_load_dwordx4 v[10:13], v[10:11], off
	v_add_u32_e32 v154, v14, v2
	v_ashrrev_i32_e32 v155, 31, v154
	v_bfe_u32 v170, v46, 5, 1
	v_lshlrev_b64 v[14:15], 7, v[154:155]
	v_lshl_add_u64 v[14:15], s[28:29], 0, v[14:15]
	v_lshlrev_b32_e32 v2, 4, v170
	s_lshl_b32 s36, s20, 7
	v_lshl_add_u64 v[36:37], v[14:15], 0, v[2:3]
	s_add_u32 s28, s27, s36
	v_lshlrev_b32_e32 v2, 4, v46
	s_addc_u32 s29, s34, 0
	v_and_b32_e32 v2, 0x70, v2
	v_lshl_add_u64 v[26:27], s[28:29], 0, v[2:3]
	v_ashrrev_i32_e32 v33, 3, v46
	s_movk_i32 s34, 0x2200
	v_mad_i64_i32 v[38:39], s[28:29], v33, s34, v[26:27]
	s_waitcnt lgkmcnt(0)
	global_load_dwordx4 v[14:17], v[38:39], off
	v_add_u32_e32 v22, 0x200, v46
	v_add_u32_e32 v28, 0x300, v46
	v_ashrrev_i32_e32 v5, 3, v5
	v_ashrrev_i32_e32 v52, 3, v22
	v_ashrrev_i32_e32 v53, 3, v28
	v_mad_i64_i32 v[40:41], s[28:29], v5, s34, v[26:27]
	v_mad_i64_i32 v[42:43], s[28:29], v52, s34, v[26:27]
	v_mad_i64_i32 v[44:45], s[28:29], v53, s34, v[26:27]
	s_movk_i32 s28, 0x90
	s_nop 0
	v_mul_lo_u32 v171, v48, s28
	v_lshlrev_b32_e32 v172, 4, v49
	v_mul_lo_u32 v173, v50, s28
	v_add_u32_e32 v49, v171, v172
	v_lshlrev_b32_e32 v174, 4, v51
	global_load_dwordx4 v[18:21], v[40:41], off
	global_load_dwordx4 v[22:25], v[42:43], off
	global_load_dwordx4 v[26:29], v[44:45], off
	global_load_dwordx4 v[114:117], v[36:37], off
	global_load_dwordx4 v[118:121], v[36:37], off offset:32
	global_load_dwordx4 v[122:125], v[36:37], off offset:64
	global_load_dwordx4 v[126:129], v[36:37], off offset:96
	v_lshlrev_b32_e32 v54, 3, v46
	v_and_b32_e32 v175, 48, v54
	s_or_b32 s27, s35, 64
	global_load_dwordx4 v[130:133], v[38:39], off offset:128
	v_cmp_lt_i32_e32 vcc, v203, v202
	v_add_u32_e32 v4, 0x80, v4
	v_lshlrev_b32_e32 v55, 3, v170
	v_mul_u32_u24_e32 v182, 0x90, v47
	v_lshlrev_b32_e32 v184, 1, v55
	v_mov_b32_e32 v185, 0xff800000
	v_mov_b32_e32 v183, 0
	s_waitcnt vmcnt(10)
	ds_write_b128 v49, v[6:9]
	v_add_u32_e32 v6, v173, v174
	s_waitcnt vmcnt(9)
; DI f32x16 zero16() { f32x16 z; for (int i = 0; i < 16; ++i) z[i] = 0.f; return z; }
; template <int DQ>
; DI void attn_item(char* lds, const u16* __restrict__ Qb, const u16* __restrict__ Kb, const u16* __restrict__ Vtb,
;                   int q0, int kt_lo, int kt_hi, float sc, u16* __restrict__ Ob, int ldo) {
;     ...
;   u32x4 rk[KPT], rv[4];
;     ...
;   f32x16 o[4];
; #pragma unroll
;   for (int i = 0; i < 4; ++i) o[i] = zero16();
;   float m_run = -INFINITY, l_run = 0.f;
;   constexpr int STG = 64 * KS + 128 * 72;
;     ...
;   ATT_LOAD(kt_lo)
;   ATT_STORE(0)
;   if (kt_lo + 1 < kt_hi) ATT_LOAD(kt_lo + 1)
;   for (int kt = kt_lo; kt < kt_hi; ++kt) {
	ds_write_b128 v6, v[10:13]
	v_lshlrev_b32_e32 v6, 2, v46
	v_and_b32_e32 v176, 4, v6
	v_or_b32_e32 v6, v175, v176
	v_lshlrev_b32_e32 v10, 1, v6
	v_lshlrev_b32_e32 v6, 1, v33
	v_lshrrev_b32_e32 v7, 2, v33
	v_and_b32_e32 v6, 24, v6
	v_and_b32_e32 v7, 4, v7
	v_and_b32_e32 v8, 0x63, v33
	v_or3_b32 v6, v7, v8, v6
	v_mul_u32_u24_e32 v177, 0x90, v6
	v_mad_u32_u24 v6, v6, s28, v10
	v_add_u32_e32 v6, 0x2000, v6
	v_lshrrev_b32_e32 v7, 2, v5
	v_and_b32_e32 v7, 4, v7
	v_and_b32_e32 v8, 0x63, v5
	v_mov_b32_e32 v12, v3
	s_waitcnt vmcnt(8)
	ds_write2_b64 v6, v[14:15], v[16:17] offset0:128 offset1:130
	v_lshlrev_b32_e32 v6, 1, v5
	v_and_b32_e32 v6, 24, v6
	v_or3_b32 v11, v7, v8, v6
	v_add_u32_e32 v6, s27, v48
	v_ashrrev_i32_e32 v7, 31, v6
	v_add_u32_e32 v8, s27, v50
	v_lshlrev_b64 v[6:7], 7, v[6:7]
	v_ashrrev_i32_e32 v9, 31, v8
	v_lshl_add_u64 v[6:7], s[6:7], 0, v[6:7]
	v_lshlrev_b64 v[8:9], 7, v[8:9]
	v_lshl_add_u64 v[6:7], v[6:7], 0, v[30:31]
	v_lshl_add_u64 v[8:9], s[6:7], 0, v[8:9]
	v_lshl_add_u64 v[8:9], v[8:9], 0, v[34:35]
	global_load_dwordx4 v[134:137], v[6:7], off
	global_load_dwordx4 v[138:141], v[8:9], off
	global_load_dwordx4 v[142:145], v[40:41], off offset:128
	global_load_dwordx4 v[146:149], v[42:43], off offset:128
	global_load_dwordx4 v[150:153], v[44:45], off offset:128
	v_mad_u32_u24 v6, v11, s28, v10
	v_add_u32_e32 v6, 0x2000, v6
	v_lshrrev_b32_e32 v7, 2, v52
	s_waitcnt vmcnt(12)
	ds_write2_b64 v6, v[18:19], v[20:21] offset0:128 offset1:130
	v_lshlrev_b32_e32 v6, 1, v52
	v_and_b32_e32 v6, 24, v6
	v_and_b32_e32 v7, 4, v7
	v_and_b32_e32 v8, 0x63, v52
	v_or3_b32 v6, v7, v8, v6
	v_mul_u32_u24_e32 v180, 0x90, v6
	v_mad_u32_u24 v6, v6, s28, v10
	v_add_u32_e32 v6, 0x2000, v6
	s_waitcnt vmcnt(11)
	ds_write2_b64 v6, v[22:23], v[24:25] offset0:128 offset1:130
	v_lshlrev_b32_e32 v6, 1, v53
	v_lshrrev_b32_e32 v7, 2, v53
	v_and_b32_e32 v6, 24, v6
	v_and_b32_e32 v7, 4, v7
	v_and_b32_e32 v8, 0x63, v53
	v_or3_b32 v6, v7, v8, v6
	v_mul_u32_u24_e32 v181, 0x90, v6
	v_mad_u32_u24 v6, v6, s28, v10
	s_or_b32 s6, s26, s36
	v_add_u32_e32 v6, 0x2000, v6
	s_add_u32 s6, s6, 0x169ac100
	s_waitcnt vmcnt(10)
	ds_write2_b64 v6, v[26:27], v[28:29] offset0:128 offset1:130
	v_cndmask_b32_e32 v6, v250, v203, vcc
	s_addc_u32 s7, s25, 0
	v_lshlrev_b32_e32 v178, 2, v6
	v_mov_b64_e32 v[6:7], s[6:7]
	v_mad_i64_i32 v[156:157], s[6:7], v53, s34, v[6:7]
	v_mad_i64_i32 v[158:159], s[6:7], v52, s34, v[6:7]
	v_mad_i64_i32 v[160:161], s[6:7], v5, s34, v[6:7]
	v_mad_i64_i32 v[162:163], s[6:7], v33, s34, v[6:7]
	v_add_u32_e32 v6, 0x80, v32
	s_add_u32 s6, s24, 0x18bac000
	v_ashrrev_i32_e32 v7, 31, v6
	v_ashrrev_i32_e32 v5, 31, v4
	s_addc_u32 s7, s23, 0
	v_lshlrev_b64 v[6:7], 7, v[6:7]
	v_lshlrev_b64 v[4:5], 7, v[4:5]
	v_lshl_add_u64 v[6:7], s[6:7], 0, v[6:7]
	v_lshl_add_u64 v[4:5], s[6:7], 0, v[4:5]
	v_mov_b32_e32 v16, v3
	v_mov_b32_e32 v17, v3
	v_mul_u32_u24_e32 v179, 0x90, v11
	v_or_b32_e32 v156, v156, v2
	v_or_b32_e32 v158, v158, v2
	v_or_b32_e32 v160, v160, v2
	v_or_b32_e32 v162, v162, v2
	v_lshl_add_u64 v[164:165], v[6:7], 0, v[34:35]
	v_lshl_add_u64 v[168:169], v[4:5], 0, v[30:31]
	v_mov_b32_e32 v2, v3
	v_mov_b32_e32 v4, v3
	v_mov_b32_e32 v5, v3
	v_mov_b32_e32 v6, v3
	v_mov_b32_e32 v7, v3
	v_mov_b32_e32 v8, v3
	v_mov_b32_e32 v9, v3
	v_mov_b32_e32 v10, v3
	v_mov_b32_e32 v11, v3
	v_mov_b32_e32 v13, v3
	v_mov_b32_e32 v14, v3
	v_mov_b32_e32 v15, v3
	v_mov_b64_e32 v[32:33], v[16:17]
	v_mov_b64_e32 v[48:49], v[16:17]
	v_mov_b64_e32 v[64:65], v[16:17]
	v_mov_b64_e32 v[80:81], v[16:17]
	v_mov_b64_e32 v[30:31], v[14:15]
	v_mov_b64_e32 v[28:29], v[12:13]
	v_mov_b64_e32 v[26:27], v[10:11]
	v_mov_b64_e32 v[24:25], v[8:9]
	v_mov_b64_e32 v[22:23], v[6:7]
	v_mov_b64_e32 v[20:21], v[4:5]
	v_mov_b64_e32 v[18:19], v[2:3]
	v_mov_b64_e32 v[46:47], v[14:15]
	v_mov_b64_e32 v[44:45], v[12:13]
	v_mov_b64_e32 v[42:43], v[10:11]
	v_mov_b64_e32 v[40:41], v[8:9]
	v_mov_b64_e32 v[38:39], v[6:7]
	v_mov_b64_e32 v[36:37], v[4:5]
	v_mov_b64_e32 v[34:35], v[2:3]
	v_mov_b64_e32 v[62:63], v[14:15]
	v_mov_b64_e32 v[60:61], v[12:13]
	v_mov_b64_e32 v[58:59], v[10:11]
	v_mov_b64_e32 v[56:57], v[8:9]
	v_mov_b64_e32 v[54:55], v[6:7]
	v_mov_b64_e32 v[52:53], v[4:5]
	v_mov_b64_e32 v[50:51], v[2:3]
	v_mov_b64_e32 v[78:79], v[14:15]
	v_mov_b64_e32 v[76:77], v[12:13]
	v_mov_b64_e32 v[74:75], v[10:11]
	v_mov_b64_e32 v[72:73], v[8:9]
	v_mov_b64_e32 v[70:71], v[6:7]
	v_mov_b64_e32 v[68:69], v[4:5]
	v_mov_b64_e32 v[66:67], v[2:3]
	s_mov_b32 s6, s20

; DI int tid_l() { int t = threadIdx.x; asm volatile("" : "+v"(t)); return t; }
; DI f32x16 zero16() { f32x16 z; for (int i = 0; i < 16; ++i) z[i] = 0.f; return z; }
; template <int DQ>
; DI void attn_item(char* lds, const u16* __restrict__ Qb, const u16* __restrict__ Kb, const u16* __restrict__ Vtb,
;                   int q0, int kt_lo, int kt_hi, float sc, u16* __restrict__ Ob, int ldo) {
;   constexpr int KS = DQ + 8, KCH = DQ / 8, KPT = 64 * KCH / 256, NKK = DQ / 16;
;   u16* sK = (u16*)lds;
;   u16* sV = sK + 64 * KS;
;   const int tid = tid_l(), lane = tid & 63, w = tid >> 6, l31 = lane & 31, h = lane >> 5;
;   bf16x8 qf[NKK];
;   {
;     const u16* qrow = Qb + (size_t)(q0 + w * 32 + l31) * DQ + h * 8;
; #pragma unroll
;     for (int kk = 0; kk < NKK; ++kk) qf[kk] = *(const bf16x8*)(qrow + kk * 16);
;   }
;   u32x4 rk[KPT], rv[4];
;     ...
;   f32x16 o[4];
; #pragma unroll
;   for (int i = 0; i < 4; ++i) o[i] = zero16();
;   float m_run = -INFINITY, l_run = 0.f;
;   constexpr int STG = 64 * KS + 128 * 72;
;     ...
;   ATT_LOAD(kt_lo)
;   ATT_STORE(0)
;   if (kt_lo + 1 < kt_hi) ATT_LOAD(kt_lo + 1)
; DI void ph_attn(const Params& p, char* lds, bool need_ctx) {
;     ...
;       const int hm = head - 8;
;       const u16* Q = isl ? (const u16*)(ws + OFF_QM) + (size_t)(b * 4 + hm) * 4096 * 96 : (const u16*)(ws + OFF_QMC) + (size_t)(b * 4 + hm) * 256 * 96;
;       const u16* K = (const u16*)(ws + OFF_KM) + (size_t)(b * 4 + hm) * KPOS * 96;
;       const u16* V = (const u16*)(ws + OFF_VTM) + (size_t)(b * 4 + hm) * 128 * KPOS;
;       attn_item<96>(lds, Q, K, V, qb * 128, kt_lo, kt_hi, sm, mix + orow0 * D + 512 + hm * 128, D);
.LBB0_644:
	s_and_b64 vcc, exec, s[6:7]
	s_cbranch_vccz .LBB0_625
	v_mov_b32_e32 v50, v0
	s_mov_b32 s27, 0x2aaaaaab
	v_and_b32_e32 v51, 31, v50
	v_ashrrev_i32_e32 v2, 1, v50
	v_and_b32_e32 v2, 0xffffffe0, v2
	v_lshl_or_b32 v4, s21, 7, v51
	v_add_u32_e32 v168, v4, v2
	v_mul_hi_i32 v2, v50, s27
	v_lshrrev_b32_e32 v4, 31, v2
	v_ashrrev_i32_e32 v2, 1, v2
	s_sub_i32 s5, 3, s22
	s_lshl_b32 s4, s4, 2
	v_add_u32_e32 v52, v2, v4
	s_add_i32 s6, s4, s5
	v_mul_lo_u32 v2, v52, 12
	s_and_b64 s[2:3], s[2:3], exec
	v_sub_u32_e32 v53, v50, v2
	s_mov_b32 s3, 0x127cc000
	v_lshlrev_b32_e32 v6, 3, v53
	v_add_u32_e32 v20, 0x100, v50
	s_mov_b32 s2, 0xc0000
	s_cselect_b32 s3, s3, 0x13fcc000
	v_ashrrev_i32_e32 v7, 31, v6
	v_mul_hi_i32 v2, v20, s27
	s_cselect_b32 s2, s2, 0xc000
	s_add_u32 s3, s30, s3
	v_lshlrev_b64 v[34:35], 1, v[6:7]
	v_lshrrev_b32_e32 v6, 31, v2
	v_ashrrev_i32_e32 v2, 1, v2
	s_addc_u32 s4, s31, 0
	s_mul_hi_i32 s7, s2, s6
	s_mul_i32 s2, s2, s6
	v_add_u32_e32 v55, v2, v6
	s_add_u32 s22, s3, s2
	v_mul_lo_u32 v2, v55, 12
	s_waitcnt vmcnt(1)
	v_add_u32_e32 v24, 0x200, v50
	s_addc_u32 s23, s4, s7
	s_mul_i32 s3, s6, 0xcc000
	v_sub_u32_e32 v56, v20, v2
	v_mul_hi_i32 v2, v24, s27
	s_mul_hi_i32 s2, s6, 0xcc000
	s_add_u32 s24, s16, s3
	v_lshrrev_b32_e32 v12, 31, v2
	v_ashrrev_i32_e32 v2, 1, v2
	s_addc_u32 s25, s17, s2
	s_mul_hi_i32 s4, s6, 0x110000
	s_mul_i32 s6, s6, 0x110000
	v_add_u32_e32 v58, v2, v12
	s_add_u32 s7, s18, s6
	v_mul_lo_u32 v2, v58, 12
	s_addc_u32 s26, s19, s4
	s_lshl_b32 s21, s20, 6
	v_lshlrev_b32_e32 v8, 3, v56
	v_sub_u32_e32 v59, v24, v2
	v_add_u32_e32 v54, s21, v52
	v_mov_b64_e32 v[32:33], s[24:25]
	s_movk_i32 s28, 0xc0
	v_add_u32_e32 v57, s21, v55
	v_ashrrev_i32_e32 v9, 31, v8
	v_lshlrev_b32_e32 v14, 3, v59
	v_mad_i64_i32 v[4:5], s[24:25], v54, s28, v[32:33]
	v_mad_i64_i32 v[6:7], s[24:25], v57, s28, v[32:33]
	v_lshlrev_b64 v[36:37], 1, v[8:9]
	v_add_u32_e32 v60, s21, v58
	v_ashrrev_i32_e32 v15, 31, v14
	v_lshl_add_u64 v[4:5], v[4:5], 0, v[34:35]
	v_lshl_add_u64 v[8:9], v[6:7], 0, v[36:37]
	v_mad_i64_i32 v[12:13], s[24:25], v60, s28, v[32:33]
	v_lshlrev_b64 v[38:39], 1, v[14:15]
	global_load_dwordx4 v[4:7], v[4:5], off
	s_nop 0
	global_load_dwordx4 v[8:11], v[8:9], off
	v_lshl_add_u64 v[12:13], v[12:13], 0, v[38:39]
	global_load_dwordx4 v[12:15], v[12:13], off
	v_bfe_u32 v184, v50, 5, 1
	s_waitcnt lgkmcnt(0)
	v_mov_b64_e32 v[16:17], s[22:23]
	v_mad_i64_i32 v[16:17], s[22:23], v168, s28, v[16:17]
	v_lshlrev_b32_e32 v2, 4, v184
	s_lshl_b32 s24, s20, 7
	v_lshl_add_u64 v[40:41], v[16:17], 0, v[2:3]
	s_add_u32 s22, s7, s24
	v_lshlrev_b32_e32 v2, 4, v50
	s_addc_u32 s23, s26, 0
	v_and_b32_e32 v2, 0x70, v2
	v_lshl_add_u64 v[28:29], s[22:23], 0, v[2:3]
	v_ashrrev_i32_e32 v61, 3, v50
	s_movk_i32 s26, 0x2200
	v_mad_i64_i32 v[42:43], s[22:23], v61, s26, v[28:29]
	global_load_dwordx4 v[16:19], v[42:43], off
	v_add_u32_e32 v30, 0x300, v50
	v_ashrrev_i32_e32 v62, 3, v20
	v_ashrrev_i32_e32 v63, 3, v24
	v_ashrrev_i32_e32 v65, 3, v30
	s_movk_i32 s7, 0xd0
	v_mad_i64_i32 v[44:45], s[22:23], v62, s26, v[28:29]
	v_mad_i64_i32 v[46:47], s[22:23], v63, s26, v[28:29]
	v_mad_i64_i32 v[48:49], s[22:23], v65, s26, v[28:29]
	v_mul_lo_u32 v185, v52, s7
	v_lshlrev_b32_e32 v186, 4, v53
	global_load_dwordx4 v[20:23], v[44:45], off
	global_load_dwordx4 v[24:27], v[46:47], off
	global_load_dwordx4 v[114:117], v[40:41], off
	global_load_dwordx4 v[118:121], v[40:41], off offset:32
	global_load_dwordx4 v[122:125], v[40:41], off offset:64
	global_load_dwordx4 v[126:129], v[40:41], off offset:96
	global_load_dwordx4 v[28:31], v[48:49], off
	global_load_dwordx4 v[130:133], v[40:41], off offset:128
	global_load_dwordx4 v[134:137], v[40:41], off offset:160
	v_add_u32_e32 v41, v185, v186
	v_mul_lo_u32 v187, v55, s7
	v_lshlrev_b32_e32 v188, 4, v56
	v_mul_lo_u32 v189, v58, s7
	v_lshlrev_b32_e32 v190, 4, v59
	v_lshlrev_b32_e32 v40, 3, v50
	v_and_b32_e32 v191, 48, v40
	s_movk_i32 s25, 0x90
	s_or_b32 s7, s21, 64
	s_or_b32 s6, s6, s24
	v_cmp_lt_i32_e32 vcc, v203, v202
	s_add_u32 s6, s6, 0x147ac100
	v_lshlrev_b32_e32 v64, 3, v184
	v_mul_u32_u24_e32 v220, 0xd0, v51
	v_mul_u32_u24_e32 v221, 0x90, v51
	v_lshlrev_b32_e32 v223, 1, v64
	v_ashrrev_i32_e32 v169, 31, v168
	v_mov_b32_e32 v224, 0xff800000
	v_mov_b32_e32 v222, 0
	s_waitcnt vmcnt(12)
	ds_write_b128 v41, v[4:7]
	v_add_u32_e32 v4, v187, v188
	s_waitcnt vmcnt(11)
	ds_write_b128 v4, v[8:11]
	v_add_u32_e32 v4, v189, v190
	s_waitcnt vmcnt(10)
; template <int DQ>
; DI void attn_item(char* lds, const u16* __restrict__ Qb, const u16* __restrict__ Kb, const u16* __restrict__ Vtb,
;                   int q0, int kt_lo, int kt_hi, float sc, u16* __restrict__ Ob, int ldo) {
;     ...
;   ATT_LOAD(kt_lo)
;   ATT_STORE(0)
;   if (kt_lo + 1 < kt_hi) ATT_LOAD(kt_lo + 1)
;   for (int kt = kt_lo; kt < kt_hi; ++kt) {
	ds_write_b128 v4, v[12:15]
	v_lshlrev_b32_e32 v4, 2, v50
	v_and_b32_e32 v192, 4, v4
	v_or_b32_e32 v4, v191, v192
	v_lshlrev_b32_e32 v10, 1, v4
	v_lshlrev_b32_e32 v4, 1, v61
	v_lshrrev_b32_e32 v5, 2, v61
	v_and_b32_e32 v4, 24, v4
	v_and_b32_e32 v5, 4, v5
	v_and_b32_e32 v6, 0x63, v61
	v_or3_b32 v4, v5, v6, v4
	v_mul_u32_u24_e32 v193, 0x90, v4
	v_mad_u32_u24 v4, v4, s25, v10
	v_add_u32_e32 v4, 0x3000, v4
	v_lshrrev_b32_e32 v5, 2, v62
	v_and_b32_e32 v5, 4, v5
	s_waitcnt vmcnt(9)
	ds_write2_b64 v4, v[16:17], v[18:19] offset0:128 offset1:130
	v_lshlrev_b32_e32 v4, 1, v62
	v_and_b32_e32 v4, 24, v4
	v_and_b32_e32 v6, 0x63, v62
	v_or3_b32 v4, v5, v6, v4
	v_mul_u32_u24_e32 v194, 0x90, v4
	v_mad_u32_u24 v4, v4, s25, v10
	v_add_u32_e32 v6, s7, v55
	v_add_u32_e32 v11, 0x3000, v4
	v_add_u32_e32 v4, s7, v52
	v_mad_i64_i32 v[6:7], s[22:23], v6, s28, v[32:33]
	v_add_u32_e32 v8, s7, v58
	v_mad_i64_i32 v[4:5], s[22:23], v4, s28, v[32:33]
	v_lshl_add_u64 v[6:7], v[6:7], 0, v[36:37]
	v_mad_i64_i32 v[8:9], s[22:23], v8, s28, v[32:33]
	v_lshl_add_u64 v[4:5], v[4:5], 0, v[34:35]
	v_lshl_add_u64 v[8:9], v[8:9], 0, v[38:39]
	global_load_dwordx4 v[138:141], v[6:7], off
	global_load_dwordx4 v[146:149], v[8:9], off
	global_load_dwordx4 v[150:153], v[42:43], off offset:128
	global_load_dwordx4 v[154:157], v[44:45], off offset:128
	global_load_dwordx4 v[158:161], v[46:47], off offset:128
	global_load_dwordx4 v[142:145], v[4:5], off
	global_load_dwordx4 v[162:165], v[48:49], off offset:128
	v_lshlrev_b32_e32 v4, 1, v63
	v_lshrrev_b32_e32 v5, 2, v63
	v_and_b32_e32 v4, 24, v4
	v_and_b32_e32 v5, 4, v5
	v_and_b32_e32 v6, 0x63, v63
	v_or3_b32 v4, v5, v6, v4
	v_mul_u32_u24_e32 v195, 0x90, v4
	v_mad_u32_u24 v4, v4, s25, v10
	v_add_u32_e32 v4, 0x3000, v4
	s_waitcnt vmcnt(15)
	ds_write2_b64 v11, v[20:21], v[22:23] offset0:128 offset1:130
	s_waitcnt vmcnt(14)
	ds_write2_b64 v4, v[24:25], v[26:27] offset0:128 offset1:130
	v_lshlrev_b32_e32 v4, 1, v65
	v_lshrrev_b32_e32 v5, 2, v65
	v_and_b32_e32 v4, 24, v4
	v_and_b32_e32 v5, 4, v5
	v_and_b32_e32 v6, 0x63, v65
	v_or3_b32 v4, v5, v6, v4
	v_mul_u32_u24_e32 v219, 0x90, v4
	v_mad_u32_u24 v4, v4, s25, v10
	v_add_u32_e32 v4, 0x3000, v4
	s_waitcnt vmcnt(9)
	ds_write2_b64 v4, v[28:29], v[30:31] offset0:128 offset1:130
	v_cndmask_b32_e32 v4, v250, v203, vcc
	s_addc_u32 s7, s4, 0
	v_lshlrev_b32_e32 v218, 2, v4
	v_mov_b64_e32 v[4:5], s[6:7]
	v_mad_i64_i32 v[170:171], s[6:7], v65, s26, v[4:5]
	v_mad_i64_i32 v[172:173], s[6:7], v63, s26, v[4:5]
	v_mad_i64_i32 v[174:175], s[6:7], v62, s26, v[4:5]
	v_mad_i64_i32 v[176:177], s[6:7], v61, s26, v[4:5]
	s_add_u32 s6, s3, 0x1adac000
	s_addc_u32 s7, s2, 0
	v_or_b32_e32 v170, v170, v2
	v_or_b32_e32 v172, v172, v2
	v_or_b32_e32 v174, v174, v2
	v_or_b32_e32 v176, v176, v2
	v_add_u32_e32 v2, 0x80, v60
	v_mov_b64_e32 v[4:5], s[6:7]
	v_mad_i64_i32 v[6:7], s[2:3], v2, s28, v[4:5]
	v_add_u32_e32 v2, 0x80, v57
	v_lshl_add_u64 v[178:179], v[6:7], 0, v[38:39]
	v_mad_i64_i32 v[6:7], s[2:3], v2, s28, v[4:5]
	v_add_u32_e32 v2, 0x80, v54
	v_mad_i64_i32 v[4:5], s[2:3], v2, s28, v[4:5]
	v_mov_b32_e32 v16, v3
	v_mov_b32_e32 v17, v3
	v_lshl_add_u64 v[180:181], v[6:7], 0, v[36:37]
	v_lshl_add_u64 v[182:183], v[4:5], 0, v[34:35]
	v_mov_b32_e32 v2, v3
	v_mov_b32_e32 v4, v3
	v_mov_b32_e32 v5, v3
	v_mov_b32_e32 v6, v3
	v_mov_b32_e32 v7, v3
	v_mov_b32_e32 v8, v3
	v_mov_b32_e32 v9, v3
	v_mov_b32_e32 v10, v3
	v_mov_b32_e32 v11, v3
	v_mov_b32_e32 v12, v3
	v_mov_b32_e32 v13, v3
	v_mov_b32_e32 v14, v3
	v_mov_b32_e32 v15, v3
	v_mov_b64_e32 v[32:33], v[16:17]
	v_mov_b64_e32 v[48:49], v[16:17]
	v_mov_b64_e32 v[64:65], v[16:17]
	v_mov_b64_e32 v[80:81], v[16:17]
	v_mov_b64_e32 v[30:31], v[14:15]
	v_mov_b64_e32 v[28:29], v[12:13]
	v_mov_b64_e32 v[26:27], v[10:11]
	v_mov_b64_e32 v[24:25], v[8:9]
	v_mov_b64_e32 v[22:23], v[6:7]
	v_mov_b64_e32 v[20:21], v[4:5]
	v_mov_b64_e32 v[18:19], v[2:3]
	v_mov_b64_e32 v[46:47], v[14:15]
	v_mov_b64_e32 v[44:45], v[12:13]
	v_mov_b64_e32 v[42:43], v[10:11]
	v_mov_b64_e32 v[40:41], v[8:9]
	v_mov_b64_e32 v[38:39], v[6:7]
	v_mov_b64_e32 v[36:37], v[4:5]
	v_mov_b64_e32 v[34:35], v[2:3]
	v_mov_b64_e32 v[62:63], v[14:15]
	v_mov_b64_e32 v[60:61], v[12:13]
	v_mov_b64_e32 v[58:59], v[10:11]
	v_mov_b64_e32 v[56:57], v[8:9]
	v_mov_b64_e32 v[54:55], v[6:7]
	v_mov_b64_e32 v[52:53], v[4:5]
	v_mov_b64_e32 v[50:51], v[2:3]
	v_mov_b64_e32 v[78:79], v[14:15]
	v_mov_b64_e32 v[76:77], v[12:13]
	v_mov_b64_e32 v[74:75], v[10:11]
	v_mov_b64_e32 v[72:73], v[8:9]
	v_mov_b64_e32 v[70:71], v[6:7]
	v_mov_b64_e32 v[68:69], v[4:5]
	v_mov_b64_e32 v[66:67], v[2:3]

; DI int bid_l() { int t = blockIdx.x; asm volatile("" : "+s"(t)); return t; }
; DI void ph_odd_prepB(const Params& p, char* lds) {
;     ...
;   const u16* z = (const u16*)(p.ws + OFF_ZO);
;   const u16* upq = (const u16*)(p.ws + OFF_UPQ); const u16* upkv = (const u16*)(p.ws + OFF_UPKV);
;   const float* rsq = (const float*)(p.ws + OFF_RSQ); const float* rskv = (const float*)(p.ws + OFF_RSKV);
;   u16* Qm = (u16*)(p.ws + OFF_QM); u16* Qmc = (u16*)(p.ws + OFF_QMC); u16* Km = (u16*)(p.ws + OFF_KM); u16* Vtm = (u16*)(p.ws + OFF_VTM);
;   for (int i = tid; i < 512; i += 256) {
;     const float inv = exp2f(-(float)(i & 7) * (13.287712379549449f / 8.f));
;     const float a = (float)(i >> 3) * inv;
;     tS[i] = sinf(a); tC[i] = cosf(a);
;   }
;   __syncthreads();
;   for (int u = bid_l() * 256 + tid; u < TA * 96; u += gridDim.x * 256) {
.LBB0_747:
	s_or_b64 exec, exec, s[8:9]
	s_add_u32 s28, s30, 0xd2cc000
	v_readlane_b32 s0, v251, 0
	s_addc_u32 s29, s31, 0
	s_waitcnt lgkmcnt(0)
	s_barrier
	s_add_u32 s8, s30, 0x8fa000
	v_lshl_add_u32 v20, s0, 8, v4
	s_mov_b32 s0, 0x330000
	s_addc_u32 s9, s31, 0
	v_cmp_gt_i32_e32 vcc, s0, v20
	s_and_saveexec_b64 s[10:11], vcc
	s_cbranch_execz .LBB0_770
	s_add_u32 s12, s30, 0xb94c000
	s_addc_u32 s13, s31, 0
	s_add_u32 s14, s30, 0x8d8000
	s_addc_u32 s15, s31, 0
	s_add_u32 s16, s30, 0x127cc000
	s_addc_u32 s17, s31, 0
	s_add_u32 s18, s30, 0x13fcc000
	s_addc_u32 s19, s31, 0
	s_add_u32 s20, s30, 0x1adac000
	s_addc_u32 s21, s31, 0
	s_mov_b64 s[22:23], 0
	s_branch .LBB0_750

; DI int bid_l() { int t = blockIdx.x; asm volatile("" : "+s"(t)); return t; }
; DI void ph_odd_prepB(const Params& p, char* lds) {
;     ...
;   for (int it = bid_l(); it < 8 * 4 * 68; it += gridDim.x) {
;     const int pt = it % 68, bh = it / 68, b = bh >> 2, hm = bh & 3;
;     const int pos0 = pt * 64;
;     const size_t rb = pos0 < 4096 ? (size_t)b * 4096 + pos0 : (size_t)TL + (size_t)b * 256 + (pos0 - 4096);
;     vt_tile(sT, upkv + rb * 768 + hm * 192 + 64, 768, rskv + rb, Vtm + (size_t)bh * 128 * KPOS + pos0);
.LBB0_770:
	s_or_b64 exec, exec, s[10:11]
	v_readlane_b32 s10, v251, 0
	s_cmpk_gt_i32 s10, 0x87f
	s_cbranch_scc1 .LBB0_777
	s_add_u32 s11, s30, 0x147ac000
	s_addc_u32 s12, s31, 0
	s_lshl_b32 s13, s10, 6
	s_branch .LBB0_773

;   template <int MF> DI void operator()(f32x16 (&acc)[MF][2], int mb, int nb, int l31, int h) const {
;     ...
;       u16* dst;
;       if (which == 0) dst = isl ? Qa + ((size_t)(b * 8 + head) * 4096 + t) * 64 : Qac + ((size_t)(b * 8 + head) * 256 + t) * 64;
;       else dst = Ka + ((size_t)(b * 8 + head) * KPOS + (isl ? t : 4096 + t)) * 64;
;       dst += 8 * h;
.LBB0_913:
	s_or_b64 exec, exec, s[14:15]
	s_cmpk_gt_u32 s21, 0x1ff
	s_cselect_b64 s[14:15], -1, 0
	v_add_u32_e32 v2, 0xffff8000, v89
	v_and_or_b32 v70, s18, 3, v97
	v_lshrrev_b32_e32 v84, 8, v2
	v_ashrrev_i32_e32 v71, 12, v89
	v_and_b32_e32 v83, 0xdf, v88
	s_mov_b64 s[16:17], -1
	s_and_b64 vcc, exec, s[14:15]
	s_cbranch_vccz .LBB0_915
	v_cndmask_b32_e64 v2, v84, v71, s[2:3]
	v_lshl_or_b32 v68, v2, 3, v70
	v_or_b32_e32 v2, 0x1000, v83
	v_cndmask_b32_e64 v2, v2, v90, s[2:3]
	s_movk_i32 s2, 0x1100
	v_mad_i64_i32 v[68:69], s[2:3], v68, s2, v[2:3]
	v_lshlrev_b64 v[68:69], 7, v[68:69]
	s_add_u32 s98, s4, 0x4400000
	s_addc_u32 s99, s5, 0
	v_lshl_add_u64 v[68:69], s[98:99], 0, v[68:69]
	s_mov_b64 s[16:17], 0

; DI unsigned pack2(float a, float b) { f2_t v = {a, b}; return __builtin_bit_cast(unsigned, __builtin_convertvector(v, bf2_t)); }
;   template <int MF> DI void operator()(f32x16 (&acc)[MF][2], int mb, int nb, int l31, int h) const {
;     ...
;       u16* dst;
;       if (which == 0) dst = isl ? Qa + ((size_t)(b * 8 + head) * 4096 + t) * 64 : Qac + ((size_t)(b * 8 + head) * 256 + t) * 64;
;       else dst = Ka + ((size_t)(b * 8 + head) * KPOS + (isl ? t : 4096 + t)) * 64;
;       dst += 8 * h;
; #pragma unroll
;       for (int g4 = 0; g4 < 4; ++g4)
;         *(u32x4*)(dst + 16 * g4) = (u32x4){pack2(x[g4][0], x[g4][1]), pack2(x[g4][2], x[g4][3]), pack2(x[g4][4], x[g4][5]), pack2(x[g4][6], x[g4][7])};
.LBB0_923:
	s_or_b64 exec, exec, s[16:17]
	v_add_u32_e32 v36, 0xffff8020, v89
	v_or_b32_e32 v38, 32, v88
	v_lshrrev_b32_e32 v39, 8, v36
	s_andn2_b64 vcc, exec, s[14:15]
	s_mov_b64 s[14:15], -1
	s_cbranch_vccnz .LBB0_925
	v_cndmask_b32_e64 v36, v39, v71, s[2:3]
	s_movk_i32 s14, 0x1000
	v_lshl_or_b32 v40, v36, 3, v70
	v_or_b32_sdwa v36, v38, s14 dst_sel:DWORD dst_unused:UNUSED_PAD src0_sel:BYTE_0 src1_sel:DWORD
	v_cndmask_b32_e64 v36, v36, v44, s[2:3]
	v_mov_b32_e32 v37, v3
	s_movk_i32 s2, 0x1100
	v_mad_i64_i32 v[36:37], s[2:3], v40, s2, v[36:37]
	v_lshlrev_b64 v[36:37], 7, v[36:37]
	s_add_u32 s98, s4, 0x4400000
	s_addc_u32 s99, s5, 0
	v_lshl_add_u64 v[36:37], s[98:99], 0, v[36:37]
	s_mov_b64 s[14:15], 0
